# v91 + skinny5: skinny_sample K-loops as a five-stage software pipeline (vmcnt(16), sets v48-v127)
# speedup vs baseline: 1.0152x; 1.0152x over previous
.LBB0_526:
	s_add_i32 s100, s24, 0x0
	s_ashr_i32 s101, s100, 31
	s_lshl_b64 s[100:101], s[100:101], 1
	v_lshl_add_u64 v[48:49], v[18:19], 0, s[100:101]
	v_lshl_add_u64 v[52:53], v[22:23], 0, s[100:101]
	v_lshl_add_u64 v[56:57], v[20:21], 0, s[100:101]
	v_lshl_add_u64 v[60:61], v[24:25], 0, s[100:101]
	global_load_dwordx4 v[48:51], v[48:49], off
	global_load_dwordx4 v[52:55], v[52:53], off
	global_load_dwordx4 v[56:59], v[56:57], off
	global_load_dwordx4 v[60:63], v[60:61], off
	s_cmp_gt_i32 s21, 47
	s_cbranch_scc1 .Lmy_sv0_tail4
	s_add_i32 s100, s24, 0x100
	s_ashr_i32 s101, s100, 31
	s_lshl_b64 s[100:101], s[100:101], 1
	v_lshl_add_u64 v[64:65], v[18:19], 0, s[100:101]
	v_lshl_add_u64 v[68:69], v[22:23], 0, s[100:101]
	v_lshl_add_u64 v[72:73], v[20:21], 0, s[100:101]
	v_lshl_add_u64 v[76:77], v[24:25], 0, s[100:101]
	global_load_dwordx4 v[64:67], v[64:65], off
	global_load_dwordx4 v[68:71], v[68:69], off
	global_load_dwordx4 v[72:75], v[72:73], off
	global_load_dwordx4 v[76:79], v[76:77], off
	s_cmp_gt_i32 s21, 39
	s_cbranch_scc1 .Lmy_sv0_tail4
	s_add_i32 s100, s24, 0x200
	s_ashr_i32 s101, s100, 31
	s_lshl_b64 s[100:101], s[100:101], 1
	v_lshl_add_u64 v[80:81], v[18:19], 0, s[100:101]
	v_lshl_add_u64 v[84:85], v[22:23], 0, s[100:101]
	v_lshl_add_u64 v[88:89], v[20:21], 0, s[100:101]
	v_lshl_add_u64 v[92:93], v[24:25], 0, s[100:101]
	global_load_dwordx4 v[80:83], v[80:81], off
	global_load_dwordx4 v[84:87], v[84:85], off
	global_load_dwordx4 v[88:91], v[88:89], off
	global_load_dwordx4 v[92:95], v[92:93], off
	s_cmp_gt_i32 s21, 31
	s_cbranch_scc1 .Lmy_sv0_tail4
	s_add_i32 s100, s24, 0x300
	s_ashr_i32 s101, s100, 31
	s_lshl_b64 s[100:101], s[100:101], 1
	v_lshl_add_u64 v[96:97], v[18:19], 0, s[100:101]
	v_lshl_add_u64 v[100:101], v[22:23], 0, s[100:101]
	v_lshl_add_u64 v[104:105], v[20:21], 0, s[100:101]
	v_lshl_add_u64 v[108:109], v[24:25], 0, s[100:101]
	global_load_dwordx4 v[96:99], v[96:97], off
	global_load_dwordx4 v[100:103], v[100:101], off
	global_load_dwordx4 v[104:107], v[104:105], off
	global_load_dwordx4 v[108:111], v[108:109], off
	s_cmp_gt_i32 s21, 23
	s_cbranch_scc1 .Lmy_sv0_tail4
	s_add_i32 s100, s24, 0x400
	s_ashr_i32 s101, s100, 31
	s_lshl_b64 s[100:101], s[100:101], 1
	v_lshl_add_u64 v[112:113], v[18:19], 0, s[100:101]
	v_lshl_add_u64 v[116:117], v[22:23], 0, s[100:101]
	v_lshl_add_u64 v[120:121], v[20:21], 0, s[100:101]
	v_lshl_add_u64 v[124:125], v[24:25], 0, s[100:101]
	global_load_dwordx4 v[112:115], v[112:113], off
	global_load_dwordx4 v[116:119], v[116:117], off
	global_load_dwordx4 v[120:123], v[120:121], off
	global_load_dwordx4 v[124:127], v[124:125], off
.Lmy_sv0_loop:
	s_waitcnt vmcnt(16)
	v_mfma_f32_16x16x32_bf16 v[14:17], v[48:51], v[56:59], v[14:17]
	v_mfma_f32_16x16x32_bf16 v[10:13], v[52:55], v[56:59], v[10:13]
	v_mfma_f32_16x16x32_bf16 v[6:9], v[48:51], v[60:63], v[6:9]
	v_mfma_f32_16x16x32_bf16 v[2:5], v[52:55], v[60:63], v[2:5]
	s_add_i32 s21, s21, 8
	s_addk_i32 s24, 0x100
	s_cmp_gt_i32 s21, 55
	s_cbranch_scc1 .Lmy_sv0_done
	s_cmp_gt_i32 s21, 23
	s_cbranch_scc1 .Lmy_sv0_tail0
	s_add_i32 s100, s24, 0x400
	s_ashr_i32 s101, s100, 31
	s_lshl_b64 s[100:101], s[100:101], 1
	v_lshl_add_u64 v[48:49], v[18:19], 0, s[100:101]
	v_lshl_add_u64 v[52:53], v[22:23], 0, s[100:101]
	v_lshl_add_u64 v[56:57], v[20:21], 0, s[100:101]
	v_lshl_add_u64 v[60:61], v[24:25], 0, s[100:101]
	global_load_dwordx4 v[48:51], v[48:49], off
	global_load_dwordx4 v[52:55], v[52:53], off
	global_load_dwordx4 v[56:59], v[56:57], off
	global_load_dwordx4 v[60:63], v[60:61], off
	s_waitcnt vmcnt(16)
	v_mfma_f32_16x16x32_bf16 v[14:17], v[64:67], v[72:75], v[14:17]
	v_mfma_f32_16x16x32_bf16 v[10:13], v[68:71], v[72:75], v[10:13]
	v_mfma_f32_16x16x32_bf16 v[6:9], v[64:67], v[76:79], v[6:9]
	v_mfma_f32_16x16x32_bf16 v[2:5], v[68:71], v[76:79], v[2:5]
	s_add_i32 s21, s21, 8
	s_addk_i32 s24, 0x100
	s_cmp_gt_i32 s21, 55
	s_cbranch_scc1 .Lmy_sv0_done
	s_cmp_gt_i32 s21, 23
	s_cbranch_scc1 .Lmy_sv0_tail1
	s_add_i32 s100, s24, 0x400
	s_ashr_i32 s101, s100, 31
	s_lshl_b64 s[100:101], s[100:101], 1
	v_lshl_add_u64 v[64:65], v[18:19], 0, s[100:101]
	v_lshl_add_u64 v[68:69], v[22:23], 0, s[100:101]
	v_lshl_add_u64 v[72:73], v[20:21], 0, s[100:101]
	v_lshl_add_u64 v[76:77], v[24:25], 0, s[100:101]
	global_load_dwordx4 v[64:67], v[64:65], off
	global_load_dwordx4 v[68:71], v[68:69], off
	global_load_dwordx4 v[72:75], v[72:73], off
	global_load_dwordx4 v[76:79], v[76:77], off
	s_waitcnt vmcnt(16)
	v_mfma_f32_16x16x32_bf16 v[14:17], v[80:83], v[88:91], v[14:17]
	v_mfma_f32_16x16x32_bf16 v[10:13], v[84:87], v[88:91], v[10:13]
	v_mfma_f32_16x16x32_bf16 v[6:9], v[80:83], v[92:95], v[6:9]
	v_mfma_f32_16x16x32_bf16 v[2:5], v[84:87], v[92:95], v[2:5]
	s_add_i32 s21, s21, 8
	s_addk_i32 s24, 0x100
	s_cmp_gt_i32 s21, 55
	s_cbranch_scc1 .Lmy_sv0_done
	s_cmp_gt_i32 s21, 23
	s_cbranch_scc1 .Lmy_sv0_tail2
	s_add_i32 s100, s24, 0x400
	s_ashr_i32 s101, s100, 31
	s_lshl_b64 s[100:101], s[100:101], 1
	v_lshl_add_u64 v[80:81], v[18:19], 0, s[100:101]
	v_lshl_add_u64 v[84:85], v[22:23], 0, s[100:101]
	v_lshl_add_u64 v[88:89], v[20:21], 0, s[100:101]
	v_lshl_add_u64 v[92:93], v[24:25], 0, s[100:101]
	global_load_dwordx4 v[80:83], v[80:81], off
	global_load_dwordx4 v[84:87], v[84:85], off
	global_load_dwordx4 v[88:91], v[88:89], off
	global_load_dwordx4 v[92:95], v[92:93], off
	s_waitcnt vmcnt(16)
	v_mfma_f32_16x16x32_bf16 v[14:17], v[96:99], v[104:107], v[14:17]
	v_mfma_f32_16x16x32_bf16 v[10:13], v[100:103], v[104:107], v[10:13]
	v_mfma_f32_16x16x32_bf16 v[6:9], v[96:99], v[108:111], v[6:9]
	v_mfma_f32_16x16x32_bf16 v[2:5], v[100:103], v[108:111], v[2:5]
	s_add_i32 s21, s21, 8
	s_addk_i32 s24, 0x100
	s_cmp_gt_i32 s21, 55
	s_cbranch_scc1 .Lmy_sv0_done
	s_cmp_gt_i32 s21, 23
	s_cbranch_scc1 .Lmy_sv0_tail3
	s_add_i32 s100, s24, 0x400
	s_ashr_i32 s101, s100, 31
	s_lshl_b64 s[100:101], s[100:101], 1
	v_lshl_add_u64 v[96:97], v[18:19], 0, s[100:101]
	v_lshl_add_u64 v[100:101], v[22:23], 0, s[100:101]
	v_lshl_add_u64 v[104:105], v[20:21], 0, s[100:101]
	v_lshl_add_u64 v[108:109], v[24:25], 0, s[100:101]
	global_load_dwordx4 v[96:99], v[96:97], off
	global_load_dwordx4 v[100:103], v[100:101], off
	global_load_dwordx4 v[104:107], v[104:105], off
	global_load_dwordx4 v[108:111], v[108:109], off
	s_waitcnt vmcnt(16)
	v_mfma_f32_16x16x32_bf16 v[14:17], v[112:115], v[120:123], v[14:17]
	v_mfma_f32_16x16x32_bf16 v[10:13], v[116:119], v[120:123], v[10:13]
	v_mfma_f32_16x16x32_bf16 v[6:9], v[112:115], v[124:127], v[6:9]
	v_mfma_f32_16x16x32_bf16 v[2:5], v[116:119], v[124:127], v[2:5]
	s_add_i32 s21, s21, 8
	s_addk_i32 s24, 0x100
	s_cmp_gt_i32 s21, 55
	s_cbranch_scc1 .Lmy_sv0_done
	s_cmp_gt_i32 s21, 23
	s_cbranch_scc1 .Lmy_sv0_tail4
	s_add_i32 s100, s24, 0x400
	s_ashr_i32 s101, s100, 31
	s_lshl_b64 s[100:101], s[100:101], 1
	v_lshl_add_u64 v[112:113], v[18:19], 0, s[100:101]
	v_lshl_add_u64 v[116:117], v[22:23], 0, s[100:101]
	v_lshl_add_u64 v[120:121], v[20:21], 0, s[100:101]
	v_lshl_add_u64 v[124:125], v[24:25], 0, s[100:101]
	global_load_dwordx4 v[112:115], v[112:113], off
	global_load_dwordx4 v[116:119], v[116:117], off
	global_load_dwordx4 v[120:123], v[120:121], off
	global_load_dwordx4 v[124:127], v[124:125], off
	s_branch .Lmy_sv0_loop
.Lmy_sv0_tail0:
	s_waitcnt vmcnt(0)
	v_mfma_f32_16x16x32_bf16 v[14:17], v[64:67], v[72:75], v[14:17]
	v_mfma_f32_16x16x32_bf16 v[10:13], v[68:71], v[72:75], v[10:13]
	v_mfma_f32_16x16x32_bf16 v[6:9], v[64:67], v[76:79], v[6:9]
	v_mfma_f32_16x16x32_bf16 v[2:5], v[68:71], v[76:79], v[2:5]
	s_add_i32 s21, s21, 8
	s_addk_i32 s24, 0x100
	s_cmp_gt_i32 s21, 55
	s_cbranch_scc1 .Lmy_sv0_done
	v_mfma_f32_16x16x32_bf16 v[14:17], v[80:83], v[88:91], v[14:17]
	v_mfma_f32_16x16x32_bf16 v[10:13], v[84:87], v[88:91], v[10:13]
	v_mfma_f32_16x16x32_bf16 v[6:9], v[80:83], v[92:95], v[6:9]
	v_mfma_f32_16x16x32_bf16 v[2:5], v[84:87], v[92:95], v[2:5]
	s_add_i32 s21, s21, 8
	s_addk_i32 s24, 0x100
	s_cmp_gt_i32 s21, 55
	s_cbranch_scc1 .Lmy_sv0_done
	v_mfma_f32_16x16x32_bf16 v[14:17], v[96:99], v[104:107], v[14:17]
	v_mfma_f32_16x16x32_bf16 v[10:13], v[100:103], v[104:107], v[10:13]
	v_mfma_f32_16x16x32_bf16 v[6:9], v[96:99], v[108:111], v[6:9]
	v_mfma_f32_16x16x32_bf16 v[2:5], v[100:103], v[108:111], v[2:5]
	s_add_i32 s21, s21, 8
	s_addk_i32 s24, 0x100
	s_cmp_gt_i32 s21, 55
	s_cbranch_scc1 .Lmy_sv0_done
	v_mfma_f32_16x16x32_bf16 v[14:17], v[112:115], v[120:123], v[14:17]
	v_mfma_f32_16x16x32_bf16 v[10:13], v[116:119], v[120:123], v[10:13]
	v_mfma_f32_16x16x32_bf16 v[6:9], v[112:115], v[124:127], v[6:9]
	v_mfma_f32_16x16x32_bf16 v[2:5], v[116:119], v[124:127], v[2:5]
	s_add_i32 s21, s21, 8
	s_addk_i32 s24, 0x100
	s_cmp_gt_i32 s21, 55
	s_cbranch_scc1 .Lmy_sv0_done
	s_branch .Lmy_sv0_done
.Lmy_sv0_tail1:
	s_waitcnt vmcnt(0)
	v_mfma_f32_16x16x32_bf16 v[14:17], v[80:83], v[88:91], v[14:17]
	v_mfma_f32_16x16x32_bf16 v[10:13], v[84:87], v[88:91], v[10:13]
	v_mfma_f32_16x16x32_bf16 v[6:9], v[80:83], v[92:95], v[6:9]
	v_mfma_f32_16x16x32_bf16 v[2:5], v[84:87], v[92:95], v[2:5]
	s_add_i32 s21, s21, 8
	s_addk_i32 s24, 0x100
	s_cmp_gt_i32 s21, 55
	s_cbranch_scc1 .Lmy_sv0_done
	v_mfma_f32_16x16x32_bf16 v[14:17], v[96:99], v[104:107], v[14:17]
	v_mfma_f32_16x16x32_bf16 v[10:13], v[100:103], v[104:107], v[10:13]
	v_mfma_f32_16x16x32_bf16 v[6:9], v[96:99], v[108:111], v[6:9]
	v_mfma_f32_16x16x32_bf16 v[2:5], v[100:103], v[108:111], v[2:5]
	s_add_i32 s21, s21, 8
	s_addk_i32 s24, 0x100
	s_cmp_gt_i32 s21, 55
	s_cbranch_scc1 .Lmy_sv0_done
	v_mfma_f32_16x16x32_bf16 v[14:17], v[112:115], v[120:123], v[14:17]
	v_mfma_f32_16x16x32_bf16 v[10:13], v[116:119], v[120:123], v[10:13]
	v_mfma_f32_16x16x32_bf16 v[6:9], v[112:115], v[124:127], v[6:9]
	v_mfma_f32_16x16x32_bf16 v[2:5], v[116:119], v[124:127], v[2:5]
	s_add_i32 s21, s21, 8
	s_addk_i32 s24, 0x100
	s_cmp_gt_i32 s21, 55
	s_cbranch_scc1 .Lmy_sv0_done
	v_mfma_f32_16x16x32_bf16 v[14:17], v[48:51], v[56:59], v[14:17]
	v_mfma_f32_16x16x32_bf16 v[10:13], v[52:55], v[56:59], v[10:13]
	v_mfma_f32_16x16x32_bf16 v[6:9], v[48:51], v[60:63], v[6:9]
	v_mfma_f32_16x16x32_bf16 v[2:5], v[52:55], v[60:63], v[2:5]
	s_add_i32 s21, s21, 8
	s_addk_i32 s24, 0x100
	s_cmp_gt_i32 s21, 55
	s_cbranch_scc1 .Lmy_sv0_done
	s_branch .Lmy_sv0_done
.Lmy_sv0_tail2:
	s_waitcnt vmcnt(0)
	v_mfma_f32_16x16x32_bf16 v[14:17], v[96:99], v[104:107], v[14:17]
	v_mfma_f32_16x16x32_bf16 v[10:13], v[100:103], v[104:107], v[10:13]
	v_mfma_f32_16x16x32_bf16 v[6:9], v[96:99], v[108:111], v[6:9]
	v_mfma_f32_16x16x32_bf16 v[2:5], v[100:103], v[108:111], v[2:5]
	s_add_i32 s21, s21, 8
	s_addk_i32 s24, 0x100
	s_cmp_gt_i32 s21, 55
	s_cbranch_scc1 .Lmy_sv0_done
	v_mfma_f32_16x16x32_bf16 v[14:17], v[112:115], v[120:123], v[14:17]
	v_mfma_f32_16x16x32_bf16 v[10:13], v[116:119], v[120:123], v[10:13]
	v_mfma_f32_16x16x32_bf16 v[6:9], v[112:115], v[124:127], v[6:9]
	v_mfma_f32_16x16x32_bf16 v[2:5], v[116:119], v[124:127], v[2:5]
	s_add_i32 s21, s21, 8
	s_addk_i32 s24, 0x100
	s_cmp_gt_i32 s21, 55
	s_cbranch_scc1 .Lmy_sv0_done
	v_mfma_f32_16x16x32_bf16 v[14:17], v[48:51], v[56:59], v[14:17]
	v_mfma_f32_16x16x32_bf16 v[10:13], v[52:55], v[56:59], v[10:13]
	v_mfma_f32_16x16x32_bf16 v[6:9], v[48:51], v[60:63], v[6:9]
	v_mfma_f32_16x16x32_bf16 v[2:5], v[52:55], v[60:63], v[2:5]
	s_add_i32 s21, s21, 8
	s_addk_i32 s24, 0x100
	s_cmp_gt_i32 s21, 55
	s_cbranch_scc1 .Lmy_sv0_done
	v_mfma_f32_16x16x32_bf16 v[14:17], v[64:67], v[72:75], v[14:17]
	v_mfma_f32_16x16x32_bf16 v[10:13], v[68:71], v[72:75], v[10:13]
	v_mfma_f32_16x16x32_bf16 v[6:9], v[64:67], v[76:79], v[6:9]
	v_mfma_f32_16x16x32_bf16 v[2:5], v[68:71], v[76:79], v[2:5]
	s_add_i32 s21, s21, 8
	s_addk_i32 s24, 0x100
	s_cmp_gt_i32 s21, 55
	s_cbranch_scc1 .Lmy_sv0_done
	s_branch .Lmy_sv0_done
.Lmy_sv0_tail3:
	s_waitcnt vmcnt(0)
	v_mfma_f32_16x16x32_bf16 v[14:17], v[112:115], v[120:123], v[14:17]
	v_mfma_f32_16x16x32_bf16 v[10:13], v[116:119], v[120:123], v[10:13]
	v_mfma_f32_16x16x32_bf16 v[6:9], v[112:115], v[124:127], v[6:9]
	v_mfma_f32_16x16x32_bf16 v[2:5], v[116:119], v[124:127], v[2:5]
	s_add_i32 s21, s21, 8
	s_addk_i32 s24, 0x100
	s_cmp_gt_i32 s21, 55
	s_cbranch_scc1 .Lmy_sv0_done
	v_mfma_f32_16x16x32_bf16 v[14:17], v[48:51], v[56:59], v[14:17]
	v_mfma_f32_16x16x32_bf16 v[10:13], v[52:55], v[56:59], v[10:13]
	v_mfma_f32_16x16x32_bf16 v[6:9], v[48:51], v[60:63], v[6:9]
	v_mfma_f32_16x16x32_bf16 v[2:5], v[52:55], v[60:63], v[2:5]
	s_add_i32 s21, s21, 8
	s_addk_i32 s24, 0x100
	s_cmp_gt_i32 s21, 55
	s_cbranch_scc1 .Lmy_sv0_done
	v_mfma_f32_16x16x32_bf16 v[14:17], v[64:67], v[72:75], v[14:17]
	v_mfma_f32_16x16x32_bf16 v[10:13], v[68:71], v[72:75], v[10:13]
	v_mfma_f32_16x16x32_bf16 v[6:9], v[64:67], v[76:79], v[6:9]
	v_mfma_f32_16x16x32_bf16 v[2:5], v[68:71], v[76:79], v[2:5]
	s_add_i32 s21, s21, 8
	s_addk_i32 s24, 0x100
	s_cmp_gt_i32 s21, 55
	s_cbranch_scc1 .Lmy_sv0_done
	v_mfma_f32_16x16x32_bf16 v[14:17], v[80:83], v[88:91], v[14:17]
	v_mfma_f32_16x16x32_bf16 v[10:13], v[84:87], v[88:91], v[10:13]
	v_mfma_f32_16x16x32_bf16 v[6:9], v[80:83], v[92:95], v[6:9]
	v_mfma_f32_16x16x32_bf16 v[2:5], v[84:87], v[92:95], v[2:5]
	s_add_i32 s21, s21, 8
	s_addk_i32 s24, 0x100
	s_cmp_gt_i32 s21, 55
	s_cbranch_scc1 .Lmy_sv0_done
	s_branch .Lmy_sv0_done
.Lmy_sv0_tail4:
	s_waitcnt vmcnt(0)
	v_mfma_f32_16x16x32_bf16 v[14:17], v[48:51], v[56:59], v[14:17]
	v_mfma_f32_16x16x32_bf16 v[10:13], v[52:55], v[56:59], v[10:13]
	v_mfma_f32_16x16x32_bf16 v[6:9], v[48:51], v[60:63], v[6:9]
	v_mfma_f32_16x16x32_bf16 v[2:5], v[52:55], v[60:63], v[2:5]
	s_add_i32 s21, s21, 8
	s_addk_i32 s24, 0x100
	s_cmp_gt_i32 s21, 55
	s_cbranch_scc1 .Lmy_sv0_done
	v_mfma_f32_16x16x32_bf16 v[14:17], v[64:67], v[72:75], v[14:17]
	v_mfma_f32_16x16x32_bf16 v[10:13], v[68:71], v[72:75], v[10:13]
	v_mfma_f32_16x16x32_bf16 v[6:9], v[64:67], v[76:79], v[6:9]
	v_mfma_f32_16x16x32_bf16 v[2:5], v[68:71], v[76:79], v[2:5]
	s_add_i32 s21, s21, 8
	s_addk_i32 s24, 0x100
	s_cmp_gt_i32 s21, 55
	s_cbranch_scc1 .Lmy_sv0_done
	v_mfma_f32_16x16x32_bf16 v[14:17], v[80:83], v[88:91], v[14:17]
	v_mfma_f32_16x16x32_bf16 v[10:13], v[84:87], v[88:91], v[10:13]
	v_mfma_f32_16x16x32_bf16 v[6:9], v[80:83], v[92:95], v[6:9]
	v_mfma_f32_16x16x32_bf16 v[2:5], v[84:87], v[92:95], v[2:5]
	s_add_i32 s21, s21, 8
	s_addk_i32 s24, 0x100
	s_cmp_gt_i32 s21, 55
	s_cbranch_scc1 .Lmy_sv0_done
	v_mfma_f32_16x16x32_bf16 v[14:17], v[96:99], v[104:107], v[14:17]
	v_mfma_f32_16x16x32_bf16 v[10:13], v[100:103], v[104:107], v[10:13]
	v_mfma_f32_16x16x32_bf16 v[6:9], v[96:99], v[108:111], v[6:9]
	v_mfma_f32_16x16x32_bf16 v[2:5], v[100:103], v[108:111], v[2:5]
	s_add_i32 s21, s21, 8
	s_addk_i32 s24, 0x100
	s_cmp_gt_i32 s21, 55
	s_cbranch_scc1 .Lmy_sv0_done
	s_branch .Lmy_sv0_done

.LBB0_722:
	s_add_i32 s100, s18, 0x0
	s_ashr_i32 s101, s100, 31
	s_lshl_b64 s[100:101], s[100:101], 1
	v_lshl_add_u64 v[48:49], v[18:19], 0, s[100:101]
	v_lshl_add_u64 v[52:53], v[22:23], 0, s[100:101]
	v_lshl_add_u64 v[56:57], v[20:21], 0, s[100:101]
	v_lshl_add_u64 v[60:61], v[24:25], 0, s[100:101]
	global_load_dwordx4 v[48:51], v[48:49], off
	global_load_dwordx4 v[52:55], v[52:53], off
	global_load_dwordx4 v[56:59], v[56:57], off
	global_load_dwordx4 v[60:63], v[60:61], off
	s_cmp_gt_i32 s6, 47
	s_cbranch_scc1 .Lmy_sv1_tail4
	s_add_i32 s100, s18, 0x100
	s_ashr_i32 s101, s100, 31
	s_lshl_b64 s[100:101], s[100:101], 1
	v_lshl_add_u64 v[64:65], v[18:19], 0, s[100:101]
	v_lshl_add_u64 v[68:69], v[22:23], 0, s[100:101]
	v_lshl_add_u64 v[72:73], v[20:21], 0, s[100:101]
	v_lshl_add_u64 v[76:77], v[24:25], 0, s[100:101]
	global_load_dwordx4 v[64:67], v[64:65], off
	global_load_dwordx4 v[68:71], v[68:69], off
	global_load_dwordx4 v[72:75], v[72:73], off
	global_load_dwordx4 v[76:79], v[76:77], off
	s_cmp_gt_i32 s6, 39
	s_cbranch_scc1 .Lmy_sv1_tail4
	s_add_i32 s100, s18, 0x200
	s_ashr_i32 s101, s100, 31
	s_lshl_b64 s[100:101], s[100:101], 1
	v_lshl_add_u64 v[80:81], v[18:19], 0, s[100:101]
	v_lshl_add_u64 v[84:85], v[22:23], 0, s[100:101]
	v_lshl_add_u64 v[88:89], v[20:21], 0, s[100:101]
	v_lshl_add_u64 v[92:93], v[24:25], 0, s[100:101]
	global_load_dwordx4 v[80:83], v[80:81], off
	global_load_dwordx4 v[84:87], v[84:85], off
	global_load_dwordx4 v[88:91], v[88:89], off
	global_load_dwordx4 v[92:95], v[92:93], off
	s_cmp_gt_i32 s6, 31
	s_cbranch_scc1 .Lmy_sv1_tail4
	s_add_i32 s100, s18, 0x300
	s_ashr_i32 s101, s100, 31
	s_lshl_b64 s[100:101], s[100:101], 1
	v_lshl_add_u64 v[96:97], v[18:19], 0, s[100:101]
	v_lshl_add_u64 v[100:101], v[22:23], 0, s[100:101]
	v_lshl_add_u64 v[104:105], v[20:21], 0, s[100:101]
	v_lshl_add_u64 v[108:109], v[24:25], 0, s[100:101]
	global_load_dwordx4 v[96:99], v[96:97], off
	global_load_dwordx4 v[100:103], v[100:101], off
	global_load_dwordx4 v[104:107], v[104:105], off
	global_load_dwordx4 v[108:111], v[108:109], off
	s_cmp_gt_i32 s6, 23
	s_cbranch_scc1 .Lmy_sv1_tail4
	s_add_i32 s100, s18, 0x400
	s_ashr_i32 s101, s100, 31
	s_lshl_b64 s[100:101], s[100:101], 1
	v_lshl_add_u64 v[112:113], v[18:19], 0, s[100:101]
	v_lshl_add_u64 v[116:117], v[22:23], 0, s[100:101]
	v_lshl_add_u64 v[120:121], v[20:21], 0, s[100:101]
	v_lshl_add_u64 v[124:125], v[24:25], 0, s[100:101]
	global_load_dwordx4 v[112:115], v[112:113], off
	global_load_dwordx4 v[116:119], v[116:117], off
	global_load_dwordx4 v[120:123], v[120:121], off
	global_load_dwordx4 v[124:127], v[124:125], off
.Lmy_sv1_loop:
	s_waitcnt vmcnt(16)
	v_mfma_f32_16x16x32_bf16 v[14:17], v[48:51], v[56:59], v[14:17]
	v_mfma_f32_16x16x32_bf16 v[10:13], v[52:55], v[56:59], v[10:13]
	v_mfma_f32_16x16x32_bf16 v[6:9], v[48:51], v[60:63], v[6:9]
	v_mfma_f32_16x16x32_bf16 v[2:5], v[52:55], v[60:63], v[2:5]
	s_add_i32 s6, s6, 8
	s_addk_i32 s18, 0x100
	s_cmp_gt_i32 s6, 55
	s_cbranch_scc1 .Lmy_sv1_done
	s_cmp_gt_i32 s6, 23
	s_cbranch_scc1 .Lmy_sv1_tail0
	s_add_i32 s100, s18, 0x400
	s_ashr_i32 s101, s100, 31
	s_lshl_b64 s[100:101], s[100:101], 1
	v_lshl_add_u64 v[48:49], v[18:19], 0, s[100:101]
	v_lshl_add_u64 v[52:53], v[22:23], 0, s[100:101]
	v_lshl_add_u64 v[56:57], v[20:21], 0, s[100:101]
	v_lshl_add_u64 v[60:61], v[24:25], 0, s[100:101]
	global_load_dwordx4 v[48:51], v[48:49], off
	global_load_dwordx4 v[52:55], v[52:53], off
	global_load_dwordx4 v[56:59], v[56:57], off
	global_load_dwordx4 v[60:63], v[60:61], off
	s_waitcnt vmcnt(16)
	v_mfma_f32_16x16x32_bf16 v[14:17], v[64:67], v[72:75], v[14:17]
	v_mfma_f32_16x16x32_bf16 v[10:13], v[68:71], v[72:75], v[10:13]
	v_mfma_f32_16x16x32_bf16 v[6:9], v[64:67], v[76:79], v[6:9]
	v_mfma_f32_16x16x32_bf16 v[2:5], v[68:71], v[76:79], v[2:5]
	s_add_i32 s6, s6, 8
	s_addk_i32 s18, 0x100
	s_cmp_gt_i32 s6, 55
	s_cbranch_scc1 .Lmy_sv1_done
	s_cmp_gt_i32 s6, 23
	s_cbranch_scc1 .Lmy_sv1_tail1
	s_add_i32 s100, s18, 0x400
	s_ashr_i32 s101, s100, 31
	s_lshl_b64 s[100:101], s[100:101], 1
	v_lshl_add_u64 v[64:65], v[18:19], 0, s[100:101]
	v_lshl_add_u64 v[68:69], v[22:23], 0, s[100:101]
	v_lshl_add_u64 v[72:73], v[20:21], 0, s[100:101]
	v_lshl_add_u64 v[76:77], v[24:25], 0, s[100:101]
	global_load_dwordx4 v[64:67], v[64:65], off
	global_load_dwordx4 v[68:71], v[68:69], off
	global_load_dwordx4 v[72:75], v[72:73], off
	global_load_dwordx4 v[76:79], v[76:77], off
	s_waitcnt vmcnt(16)
	v_mfma_f32_16x16x32_bf16 v[14:17], v[80:83], v[88:91], v[14:17]
	v_mfma_f32_16x16x32_bf16 v[10:13], v[84:87], v[88:91], v[10:13]
	v_mfma_f32_16x16x32_bf16 v[6:9], v[80:83], v[92:95], v[6:9]
	v_mfma_f32_16x16x32_bf16 v[2:5], v[84:87], v[92:95], v[2:5]
	s_add_i32 s6, s6, 8
	s_addk_i32 s18, 0x100
	s_cmp_gt_i32 s6, 55
	s_cbranch_scc1 .Lmy_sv1_done
	s_cmp_gt_i32 s6, 23
	s_cbranch_scc1 .Lmy_sv1_tail2
	s_add_i32 s100, s18, 0x400
	s_ashr_i32 s101, s100, 31
	s_lshl_b64 s[100:101], s[100:101], 1
	v_lshl_add_u64 v[80:81], v[18:19], 0, s[100:101]
	v_lshl_add_u64 v[84:85], v[22:23], 0, s[100:101]
	v_lshl_add_u64 v[88:89], v[20:21], 0, s[100:101]
	v_lshl_add_u64 v[92:93], v[24:25], 0, s[100:101]
	global_load_dwordx4 v[80:83], v[80:81], off
	global_load_dwordx4 v[84:87], v[84:85], off
	global_load_dwordx4 v[88:91], v[88:89], off
	global_load_dwordx4 v[92:95], v[92:93], off
	s_waitcnt vmcnt(16)
	v_mfma_f32_16x16x32_bf16 v[14:17], v[96:99], v[104:107], v[14:17]
	v_mfma_f32_16x16x32_bf16 v[10:13], v[100:103], v[104:107], v[10:13]
	v_mfma_f32_16x16x32_bf16 v[6:9], v[96:99], v[108:111], v[6:9]
	v_mfma_f32_16x16x32_bf16 v[2:5], v[100:103], v[108:111], v[2:5]
	s_add_i32 s6, s6, 8
	s_addk_i32 s18, 0x100
	s_cmp_gt_i32 s6, 55
	s_cbranch_scc1 .Lmy_sv1_done
	s_cmp_gt_i32 s6, 23
	s_cbranch_scc1 .Lmy_sv1_tail3
	s_add_i32 s100, s18, 0x400
	s_ashr_i32 s101, s100, 31
	s_lshl_b64 s[100:101], s[100:101], 1
	v_lshl_add_u64 v[96:97], v[18:19], 0, s[100:101]
	v_lshl_add_u64 v[100:101], v[22:23], 0, s[100:101]
	v_lshl_add_u64 v[104:105], v[20:21], 0, s[100:101]
	v_lshl_add_u64 v[108:109], v[24:25], 0, s[100:101]
	global_load_dwordx4 v[96:99], v[96:97], off
	global_load_dwordx4 v[100:103], v[100:101], off
	global_load_dwordx4 v[104:107], v[104:105], off
	global_load_dwordx4 v[108:111], v[108:109], off
	s_waitcnt vmcnt(16)
	v_mfma_f32_16x16x32_bf16 v[14:17], v[112:115], v[120:123], v[14:17]
	v_mfma_f32_16x16x32_bf16 v[10:13], v[116:119], v[120:123], v[10:13]
	v_mfma_f32_16x16x32_bf16 v[6:9], v[112:115], v[124:127], v[6:9]
	v_mfma_f32_16x16x32_bf16 v[2:5], v[116:119], v[124:127], v[2:5]
	s_add_i32 s6, s6, 8
	s_addk_i32 s18, 0x100
	s_cmp_gt_i32 s6, 55
	s_cbranch_scc1 .Lmy_sv1_done
	s_cmp_gt_i32 s6, 23
	s_cbranch_scc1 .Lmy_sv1_tail4
	s_add_i32 s100, s18, 0x400
	s_ashr_i32 s101, s100, 31
	s_lshl_b64 s[100:101], s[100:101], 1
	v_lshl_add_u64 v[112:113], v[18:19], 0, s[100:101]
	v_lshl_add_u64 v[116:117], v[22:23], 0, s[100:101]
	v_lshl_add_u64 v[120:121], v[20:21], 0, s[100:101]
	v_lshl_add_u64 v[124:125], v[24:25], 0, s[100:101]
	global_load_dwordx4 v[112:115], v[112:113], off
	global_load_dwordx4 v[116:119], v[116:117], off
	global_load_dwordx4 v[120:123], v[120:121], off
	global_load_dwordx4 v[124:127], v[124:125], off
	s_branch .Lmy_sv1_loop
.Lmy_sv1_tail0:
	s_waitcnt vmcnt(0)
	v_mfma_f32_16x16x32_bf16 v[14:17], v[64:67], v[72:75], v[14:17]
	v_mfma_f32_16x16x32_bf16 v[10:13], v[68:71], v[72:75], v[10:13]
	v_mfma_f32_16x16x32_bf16 v[6:9], v[64:67], v[76:79], v[6:9]
	v_mfma_f32_16x16x32_bf16 v[2:5], v[68:71], v[76:79], v[2:5]
	s_add_i32 s6, s6, 8
	s_addk_i32 s18, 0x100
	s_cmp_gt_i32 s6, 55
	s_cbranch_scc1 .Lmy_sv1_done
	v_mfma_f32_16x16x32_bf16 v[14:17], v[80:83], v[88:91], v[14:17]
	v_mfma_f32_16x16x32_bf16 v[10:13], v[84:87], v[88:91], v[10:13]
	v_mfma_f32_16x16x32_bf16 v[6:9], v[80:83], v[92:95], v[6:9]
	v_mfma_f32_16x16x32_bf16 v[2:5], v[84:87], v[92:95], v[2:5]
	s_add_i32 s6, s6, 8
	s_addk_i32 s18, 0x100
	s_cmp_gt_i32 s6, 55
	s_cbranch_scc1 .Lmy_sv1_done
	v_mfma_f32_16x16x32_bf16 v[14:17], v[96:99], v[104:107], v[14:17]
	v_mfma_f32_16x16x32_bf16 v[10:13], v[100:103], v[104:107], v[10:13]
	v_mfma_f32_16x16x32_bf16 v[6:9], v[96:99], v[108:111], v[6:9]
	v_mfma_f32_16x16x32_bf16 v[2:5], v[100:103], v[108:111], v[2:5]
	s_add_i32 s6, s6, 8
	s_addk_i32 s18, 0x100
	s_cmp_gt_i32 s6, 55
	s_cbranch_scc1 .Lmy_sv1_done
	v_mfma_f32_16x16x32_bf16 v[14:17], v[112:115], v[120:123], v[14:17]
	v_mfma_f32_16x16x32_bf16 v[10:13], v[116:119], v[120:123], v[10:13]
	v_mfma_f32_16x16x32_bf16 v[6:9], v[112:115], v[124:127], v[6:9]
	v_mfma_f32_16x16x32_bf16 v[2:5], v[116:119], v[124:127], v[2:5]
	s_add_i32 s6, s6, 8
	s_addk_i32 s18, 0x100
	s_cmp_gt_i32 s6, 55
	s_cbranch_scc1 .Lmy_sv1_done
	s_branch .Lmy_sv1_done
.Lmy_sv1_tail1:
	s_waitcnt vmcnt(0)
	v_mfma_f32_16x16x32_bf16 v[14:17], v[80:83], v[88:91], v[14:17]
	v_mfma_f32_16x16x32_bf16 v[10:13], v[84:87], v[88:91], v[10:13]
	v_mfma_f32_16x16x32_bf16 v[6:9], v[80:83], v[92:95], v[6:9]
	v_mfma_f32_16x16x32_bf16 v[2:5], v[84:87], v[92:95], v[2:5]
	s_add_i32 s6, s6, 8
	s_addk_i32 s18, 0x100
	s_cmp_gt_i32 s6, 55
	s_cbranch_scc1 .Lmy_sv1_done
	v_mfma_f32_16x16x32_bf16 v[14:17], v[96:99], v[104:107], v[14:17]
	v_mfma_f32_16x16x32_bf16 v[10:13], v[100:103], v[104:107], v[10:13]
	v_mfma_f32_16x16x32_bf16 v[6:9], v[96:99], v[108:111], v[6:9]
	v_mfma_f32_16x16x32_bf16 v[2:5], v[100:103], v[108:111], v[2:5]
	s_add_i32 s6, s6, 8
	s_addk_i32 s18, 0x100
	s_cmp_gt_i32 s6, 55
	s_cbranch_scc1 .Lmy_sv1_done
	v_mfma_f32_16x16x32_bf16 v[14:17], v[112:115], v[120:123], v[14:17]
	v_mfma_f32_16x16x32_bf16 v[10:13], v[116:119], v[120:123], v[10:13]
	v_mfma_f32_16x16x32_bf16 v[6:9], v[112:115], v[124:127], v[6:9]
	v_mfma_f32_16x16x32_bf16 v[2:5], v[116:119], v[124:127], v[2:5]
	s_add_i32 s6, s6, 8
	s_addk_i32 s18, 0x100
	s_cmp_gt_i32 s6, 55
	s_cbranch_scc1 .Lmy_sv1_done
	v_mfma_f32_16x16x32_bf16 v[14:17], v[48:51], v[56:59], v[14:17]
	v_mfma_f32_16x16x32_bf16 v[10:13], v[52:55], v[56:59], v[10:13]
	v_mfma_f32_16x16x32_bf16 v[6:9], v[48:51], v[60:63], v[6:9]
	v_mfma_f32_16x16x32_bf16 v[2:5], v[52:55], v[60:63], v[2:5]
	s_add_i32 s6, s6, 8
	s_addk_i32 s18, 0x100
	s_cmp_gt_i32 s6, 55
	s_cbranch_scc1 .Lmy_sv1_done
	s_branch .Lmy_sv1_done
.Lmy_sv1_tail2:
	s_waitcnt vmcnt(0)
	v_mfma_f32_16x16x32_bf16 v[14:17], v[96:99], v[104:107], v[14:17]
	v_mfma_f32_16x16x32_bf16 v[10:13], v[100:103], v[104:107], v[10:13]
	v_mfma_f32_16x16x32_bf16 v[6:9], v[96:99], v[108:111], v[6:9]
	v_mfma_f32_16x16x32_bf16 v[2:5], v[100:103], v[108:111], v[2:5]
	s_add_i32 s6, s6, 8
	s_addk_i32 s18, 0x100
	s_cmp_gt_i32 s6, 55
	s_cbranch_scc1 .Lmy_sv1_done
	v_mfma_f32_16x16x32_bf16 v[14:17], v[112:115], v[120:123], v[14:17]
	v_mfma_f32_16x16x32_bf16 v[10:13], v[116:119], v[120:123], v[10:13]
	v_mfma_f32_16x16x32_bf16 v[6:9], v[112:115], v[124:127], v[6:9]
	v_mfma_f32_16x16x32_bf16 v[2:5], v[116:119], v[124:127], v[2:5]
	s_add_i32 s6, s6, 8
	s_addk_i32 s18, 0x100
	s_cmp_gt_i32 s6, 55
	s_cbranch_scc1 .Lmy_sv1_done
	v_mfma_f32_16x16x32_bf16 v[14:17], v[48:51], v[56:59], v[14:17]
	v_mfma_f32_16x16x32_bf16 v[10:13], v[52:55], v[56:59], v[10:13]
	v_mfma_f32_16x16x32_bf16 v[6:9], v[48:51], v[60:63], v[6:9]
	v_mfma_f32_16x16x32_bf16 v[2:5], v[52:55], v[60:63], v[2:5]
	s_add_i32 s6, s6, 8
	s_addk_i32 s18, 0x100
	s_cmp_gt_i32 s6, 55
	s_cbranch_scc1 .Lmy_sv1_done
	v_mfma_f32_16x16x32_bf16 v[14:17], v[64:67], v[72:75], v[14:17]
	v_mfma_f32_16x16x32_bf16 v[10:13], v[68:71], v[72:75], v[10:13]
	v_mfma_f32_16x16x32_bf16 v[6:9], v[64:67], v[76:79], v[6:9]
	v_mfma_f32_16x16x32_bf16 v[2:5], v[68:71], v[76:79], v[2:5]
	s_add_i32 s6, s6, 8
	s_addk_i32 s18, 0x100
	s_cmp_gt_i32 s6, 55
	s_cbranch_scc1 .Lmy_sv1_done
	s_branch .Lmy_sv1_done
.Lmy_sv1_tail3:
	s_waitcnt vmcnt(0)
	v_mfma_f32_16x16x32_bf16 v[14:17], v[112:115], v[120:123], v[14:17]
	v_mfma_f32_16x16x32_bf16 v[10:13], v[116:119], v[120:123], v[10:13]
	v_mfma_f32_16x16x32_bf16 v[6:9], v[112:115], v[124:127], v[6:9]
	v_mfma_f32_16x16x32_bf16 v[2:5], v[116:119], v[124:127], v[2:5]
	s_add_i32 s6, s6, 8
	s_addk_i32 s18, 0x100
	s_cmp_gt_i32 s6, 55
	s_cbranch_scc1 .Lmy_sv1_done
	v_mfma_f32_16x16x32_bf16 v[14:17], v[48:51], v[56:59], v[14:17]
	v_mfma_f32_16x16x32_bf16 v[10:13], v[52:55], v[56:59], v[10:13]
	v_mfma_f32_16x16x32_bf16 v[6:9], v[48:51], v[60:63], v[6:9]
	v_mfma_f32_16x16x32_bf16 v[2:5], v[52:55], v[60:63], v[2:5]
	s_add_i32 s6, s6, 8
	s_addk_i32 s18, 0x100
	s_cmp_gt_i32 s6, 55
	s_cbranch_scc1 .Lmy_sv1_done
	v_mfma_f32_16x16x32_bf16 v[14:17], v[64:67], v[72:75], v[14:17]
	v_mfma_f32_16x16x32_bf16 v[10:13], v[68:71], v[72:75], v[10:13]
	v_mfma_f32_16x16x32_bf16 v[6:9], v[64:67], v[76:79], v[6:9]
	v_mfma_f32_16x16x32_bf16 v[2:5], v[68:71], v[76:79], v[2:5]
	s_add_i32 s6, s6, 8
	s_addk_i32 s18, 0x100
	s_cmp_gt_i32 s6, 55
	s_cbranch_scc1 .Lmy_sv1_done
	v_mfma_f32_16x16x32_bf16 v[14:17], v[80:83], v[88:91], v[14:17]
	v_mfma_f32_16x16x32_bf16 v[10:13], v[84:87], v[88:91], v[10:13]
	v_mfma_f32_16x16x32_bf16 v[6:9], v[80:83], v[92:95], v[6:9]
	v_mfma_f32_16x16x32_bf16 v[2:5], v[84:87], v[92:95], v[2:5]
	s_add_i32 s6, s6, 8
	s_addk_i32 s18, 0x100
	s_cmp_gt_i32 s6, 55
	s_cbranch_scc1 .Lmy_sv1_done
	s_branch .Lmy_sv1_done
.Lmy_sv1_tail4:
	s_waitcnt vmcnt(0)
	v_mfma_f32_16x16x32_bf16 v[14:17], v[48:51], v[56:59], v[14:17]
	v_mfma_f32_16x16x32_bf16 v[10:13], v[52:55], v[56:59], v[10:13]
	v_mfma_f32_16x16x32_bf16 v[6:9], v[48:51], v[60:63], v[6:9]
	v_mfma_f32_16x16x32_bf16 v[2:5], v[52:55], v[60:63], v[2:5]
	s_add_i32 s6, s6, 8
	s_addk_i32 s18, 0x100
	s_cmp_gt_i32 s6, 55
	s_cbranch_scc1 .Lmy_sv1_done
	v_mfma_f32_16x16x32_bf16 v[14:17], v[64:67], v[72:75], v[14:17]
	v_mfma_f32_16x16x32_bf16 v[10:13], v[68:71], v[72:75], v[10:13]
	v_mfma_f32_16x16x32_bf16 v[6:9], v[64:67], v[76:79], v[6:9]
	v_mfma_f32_16x16x32_bf16 v[2:5], v[68:71], v[76:79], v[2:5]
	s_add_i32 s6, s6, 8
	s_addk_i32 s18, 0x100
	s_cmp_gt_i32 s6, 55
	s_cbranch_scc1 .Lmy_sv1_done
	v_mfma_f32_16x16x32_bf16 v[14:17], v[80:83], v[88:91], v[14:17]
	v_mfma_f32_16x16x32_bf16 v[10:13], v[84:87], v[88:91], v[10:13]
	v_mfma_f32_16x16x32_bf16 v[6:9], v[80:83], v[92:95], v[6:9]
	v_mfma_f32_16x16x32_bf16 v[2:5], v[84:87], v[92:95], v[2:5]
	s_add_i32 s6, s6, 8
	s_addk_i32 s18, 0x100
	s_cmp_gt_i32 s6, 55
	s_cbranch_scc1 .Lmy_sv1_done
	v_mfma_f32_16x16x32_bf16 v[14:17], v[96:99], v[104:107], v[14:17]
	v_mfma_f32_16x16x32_bf16 v[10:13], v[100:103], v[104:107], v[10:13]
	v_mfma_f32_16x16x32_bf16 v[6:9], v[96:99], v[108:111], v[6:9]
	v_mfma_f32_16x16x32_bf16 v[2:5], v[100:103], v[108:111], v[2:5]
	s_add_i32 s6, s6, 8
	s_addk_i32 s18, 0x100
	s_cmp_gt_i32 s6, 55
	s_cbranch_scc1 .Lmy_sv1_done
	s_branch .Lmy_sv1_done

.LBB0_1878:
	s_add_i32 s100, s22, 0x0
	s_ashr_i32 s101, s100, 31
	s_lshl_b64 s[100:101], s[100:101], 1
	v_lshl_add_u64 v[48:49], v[20:21], 0, s[100:101]
	v_lshl_add_u64 v[52:53], v[24:25], 0, s[100:101]
	v_lshl_add_u64 v[56:57], v[22:23], 0, s[100:101]
	v_lshl_add_u64 v[60:61], v[26:27], 0, s[100:101]
	global_load_dwordx4 v[48:51], v[48:49], off
	global_load_dwordx4 v[52:55], v[52:53], off
	global_load_dwordx4 v[56:59], v[56:57], off
	global_load_dwordx4 v[60:63], v[60:61], off
	s_cmp_gt_i32 s9, 155
	s_cbranch_scc1 .Lmy_sv4_tail4
	s_add_i32 s100, s22, 0x100
	s_ashr_i32 s101, s100, 31
	s_lshl_b64 s[100:101], s[100:101], 1
	v_lshl_add_u64 v[64:65], v[20:21], 0, s[100:101]
	v_lshl_add_u64 v[68:69], v[24:25], 0, s[100:101]
	v_lshl_add_u64 v[72:73], v[22:23], 0, s[100:101]
	v_lshl_add_u64 v[76:77], v[26:27], 0, s[100:101]
	global_load_dwordx4 v[64:67], v[64:65], off
	global_load_dwordx4 v[68:71], v[68:69], off
	global_load_dwordx4 v[72:75], v[72:73], off
	global_load_dwordx4 v[76:79], v[76:77], off
	s_cmp_gt_i32 s9, 147
	s_cbranch_scc1 .Lmy_sv4_tail4
	s_add_i32 s100, s22, 0x200
	s_ashr_i32 s101, s100, 31
	s_lshl_b64 s[100:101], s[100:101], 1
	v_lshl_add_u64 v[80:81], v[20:21], 0, s[100:101]
	v_lshl_add_u64 v[84:85], v[24:25], 0, s[100:101]
	v_lshl_add_u64 v[88:89], v[22:23], 0, s[100:101]
	v_lshl_add_u64 v[92:93], v[26:27], 0, s[100:101]
	global_load_dwordx4 v[80:83], v[80:81], off
	global_load_dwordx4 v[84:87], v[84:85], off
	global_load_dwordx4 v[88:91], v[88:89], off
	global_load_dwordx4 v[92:95], v[92:93], off
	s_cmp_gt_i32 s9, 139
	s_cbranch_scc1 .Lmy_sv4_tail4
	s_add_i32 s100, s22, 0x300
	s_ashr_i32 s101, s100, 31
	s_lshl_b64 s[100:101], s[100:101], 1
	v_lshl_add_u64 v[96:97], v[20:21], 0, s[100:101]
	v_lshl_add_u64 v[100:101], v[24:25], 0, s[100:101]
	v_lshl_add_u64 v[104:105], v[22:23], 0, s[100:101]
	v_lshl_add_u64 v[108:109], v[26:27], 0, s[100:101]
	global_load_dwordx4 v[96:99], v[96:97], off
	global_load_dwordx4 v[100:103], v[100:101], off
	global_load_dwordx4 v[104:107], v[104:105], off
	global_load_dwordx4 v[108:111], v[108:109], off
	s_cmp_gt_i32 s9, 131
	s_cbranch_scc1 .Lmy_sv4_tail4
	s_add_i32 s100, s22, 0x400
	s_ashr_i32 s101, s100, 31
	s_lshl_b64 s[100:101], s[100:101], 1
	v_lshl_add_u64 v[112:113], v[20:21], 0, s[100:101]
	v_lshl_add_u64 v[116:117], v[24:25], 0, s[100:101]
	v_lshl_add_u64 v[120:121], v[22:23], 0, s[100:101]
	v_lshl_add_u64 v[124:125], v[26:27], 0, s[100:101]
	global_load_dwordx4 v[112:115], v[112:113], off
	global_load_dwordx4 v[116:119], v[116:117], off
	global_load_dwordx4 v[120:123], v[120:121], off
	global_load_dwordx4 v[124:127], v[124:125], off
.Lmy_sv4_loop:
	s_waitcnt vmcnt(16)
	v_mfma_f32_16x16x32_bf16 v[14:17], v[48:51], v[56:59], v[14:17]
	v_mfma_f32_16x16x32_bf16 v[10:13], v[52:55], v[56:59], v[10:13]
	v_mfma_f32_16x16x32_bf16 v[6:9], v[48:51], v[60:63], v[6:9]
	v_mfma_f32_16x16x32_bf16 v[2:5], v[52:55], v[60:63], v[2:5]
	s_add_i32 s9, s9, 8
	s_addk_i32 s22, 0x100
	s_cmp_gt_i32 s9, 163
	s_cbranch_scc1 .Lmy_sv4_done
	s_cmp_gt_i32 s9, 131
	s_cbranch_scc1 .Lmy_sv4_tail0
	s_add_i32 s100, s22, 0x400
	s_ashr_i32 s101, s100, 31
	s_lshl_b64 s[100:101], s[100:101], 1
	v_lshl_add_u64 v[48:49], v[20:21], 0, s[100:101]
	v_lshl_add_u64 v[52:53], v[24:25], 0, s[100:101]
	v_lshl_add_u64 v[56:57], v[22:23], 0, s[100:101]
	v_lshl_add_u64 v[60:61], v[26:27], 0, s[100:101]
	global_load_dwordx4 v[48:51], v[48:49], off
	global_load_dwordx4 v[52:55], v[52:53], off
	global_load_dwordx4 v[56:59], v[56:57], off
	global_load_dwordx4 v[60:63], v[60:61], off
	s_waitcnt vmcnt(16)
	v_mfma_f32_16x16x32_bf16 v[14:17], v[64:67], v[72:75], v[14:17]
	v_mfma_f32_16x16x32_bf16 v[10:13], v[68:71], v[72:75], v[10:13]
	v_mfma_f32_16x16x32_bf16 v[6:9], v[64:67], v[76:79], v[6:9]
	v_mfma_f32_16x16x32_bf16 v[2:5], v[68:71], v[76:79], v[2:5]
	s_add_i32 s9, s9, 8
	s_addk_i32 s22, 0x100
	s_cmp_gt_i32 s9, 163
	s_cbranch_scc1 .Lmy_sv4_done
	s_cmp_gt_i32 s9, 131
	s_cbranch_scc1 .Lmy_sv4_tail1
	s_add_i32 s100, s22, 0x400
	s_ashr_i32 s101, s100, 31
	s_lshl_b64 s[100:101], s[100:101], 1
	v_lshl_add_u64 v[64:65], v[20:21], 0, s[100:101]
	v_lshl_add_u64 v[68:69], v[24:25], 0, s[100:101]
	v_lshl_add_u64 v[72:73], v[22:23], 0, s[100:101]
	v_lshl_add_u64 v[76:77], v[26:27], 0, s[100:101]
	global_load_dwordx4 v[64:67], v[64:65], off
	global_load_dwordx4 v[68:71], v[68:69], off
	global_load_dwordx4 v[72:75], v[72:73], off
	global_load_dwordx4 v[76:79], v[76:77], off
	s_waitcnt vmcnt(16)
	v_mfma_f32_16x16x32_bf16 v[14:17], v[80:83], v[88:91], v[14:17]
	v_mfma_f32_16x16x32_bf16 v[10:13], v[84:87], v[88:91], v[10:13]
	v_mfma_f32_16x16x32_bf16 v[6:9], v[80:83], v[92:95], v[6:9]
	v_mfma_f32_16x16x32_bf16 v[2:5], v[84:87], v[92:95], v[2:5]
	s_add_i32 s9, s9, 8
	s_addk_i32 s22, 0x100
	s_cmp_gt_i32 s9, 163
	s_cbranch_scc1 .Lmy_sv4_done
	s_cmp_gt_i32 s9, 131
	s_cbranch_scc1 .Lmy_sv4_tail2
	s_add_i32 s100, s22, 0x400
	s_ashr_i32 s101, s100, 31
	s_lshl_b64 s[100:101], s[100:101], 1
	v_lshl_add_u64 v[80:81], v[20:21], 0, s[100:101]
	v_lshl_add_u64 v[84:85], v[24:25], 0, s[100:101]
	v_lshl_add_u64 v[88:89], v[22:23], 0, s[100:101]
	v_lshl_add_u64 v[92:93], v[26:27], 0, s[100:101]
	global_load_dwordx4 v[80:83], v[80:81], off
	global_load_dwordx4 v[84:87], v[84:85], off
	global_load_dwordx4 v[88:91], v[88:89], off
	global_load_dwordx4 v[92:95], v[92:93], off
	s_waitcnt vmcnt(16)
	v_mfma_f32_16x16x32_bf16 v[14:17], v[96:99], v[104:107], v[14:17]
	v_mfma_f32_16x16x32_bf16 v[10:13], v[100:103], v[104:107], v[10:13]
	v_mfma_f32_16x16x32_bf16 v[6:9], v[96:99], v[108:111], v[6:9]
	v_mfma_f32_16x16x32_bf16 v[2:5], v[100:103], v[108:111], v[2:5]
	s_add_i32 s9, s9, 8
	s_addk_i32 s22, 0x100
	s_cmp_gt_i32 s9, 163
	s_cbranch_scc1 .Lmy_sv4_done
	s_cmp_gt_i32 s9, 131
	s_cbranch_scc1 .Lmy_sv4_tail3
	s_add_i32 s100, s22, 0x400
	s_ashr_i32 s101, s100, 31
	s_lshl_b64 s[100:101], s[100:101], 1
	v_lshl_add_u64 v[96:97], v[20:21], 0, s[100:101]
	v_lshl_add_u64 v[100:101], v[24:25], 0, s[100:101]
	v_lshl_add_u64 v[104:105], v[22:23], 0, s[100:101]
	v_lshl_add_u64 v[108:109], v[26:27], 0, s[100:101]
	global_load_dwordx4 v[96:99], v[96:97], off
	global_load_dwordx4 v[100:103], v[100:101], off
	global_load_dwordx4 v[104:107], v[104:105], off
	global_load_dwordx4 v[108:111], v[108:109], off
	s_waitcnt vmcnt(16)
	v_mfma_f32_16x16x32_bf16 v[14:17], v[112:115], v[120:123], v[14:17]
	v_mfma_f32_16x16x32_bf16 v[10:13], v[116:119], v[120:123], v[10:13]
	v_mfma_f32_16x16x32_bf16 v[6:9], v[112:115], v[124:127], v[6:9]
	v_mfma_f32_16x16x32_bf16 v[2:5], v[116:119], v[124:127], v[2:5]
	s_add_i32 s9, s9, 8
	s_addk_i32 s22, 0x100
	s_cmp_gt_i32 s9, 163
	s_cbranch_scc1 .Lmy_sv4_done
	s_cmp_gt_i32 s9, 131
	s_cbranch_scc1 .Lmy_sv4_tail4
	s_add_i32 s100, s22, 0x400
	s_ashr_i32 s101, s100, 31
	s_lshl_b64 s[100:101], s[100:101], 1
	v_lshl_add_u64 v[112:113], v[20:21], 0, s[100:101]
	v_lshl_add_u64 v[116:117], v[24:25], 0, s[100:101]
	v_lshl_add_u64 v[120:121], v[22:23], 0, s[100:101]
	v_lshl_add_u64 v[124:125], v[26:27], 0, s[100:101]
	global_load_dwordx4 v[112:115], v[112:113], off
	global_load_dwordx4 v[116:119], v[116:117], off
	global_load_dwordx4 v[120:123], v[120:121], off
	global_load_dwordx4 v[124:127], v[124:125], off
	s_branch .Lmy_sv4_loop
.Lmy_sv4_tail0:
	s_waitcnt vmcnt(0)
	v_mfma_f32_16x16x32_bf16 v[14:17], v[64:67], v[72:75], v[14:17]
	v_mfma_f32_16x16x32_bf16 v[10:13], v[68:71], v[72:75], v[10:13]
	v_mfma_f32_16x16x32_bf16 v[6:9], v[64:67], v[76:79], v[6:9]
	v_mfma_f32_16x16x32_bf16 v[2:5], v[68:71], v[76:79], v[2:5]
	s_add_i32 s9, s9, 8
	s_addk_i32 s22, 0x100
	s_cmp_gt_i32 s9, 163
	s_cbranch_scc1 .Lmy_sv4_done
	v_mfma_f32_16x16x32_bf16 v[14:17], v[80:83], v[88:91], v[14:17]
	v_mfma_f32_16x16x32_bf16 v[10:13], v[84:87], v[88:91], v[10:13]
	v_mfma_f32_16x16x32_bf16 v[6:9], v[80:83], v[92:95], v[6:9]
	v_mfma_f32_16x16x32_bf16 v[2:5], v[84:87], v[92:95], v[2:5]
	s_add_i32 s9, s9, 8
	s_addk_i32 s22, 0x100
	s_cmp_gt_i32 s9, 163
	s_cbranch_scc1 .Lmy_sv4_done
	v_mfma_f32_16x16x32_bf16 v[14:17], v[96:99], v[104:107], v[14:17]
	v_mfma_f32_16x16x32_bf16 v[10:13], v[100:103], v[104:107], v[10:13]
	v_mfma_f32_16x16x32_bf16 v[6:9], v[96:99], v[108:111], v[6:9]
	v_mfma_f32_16x16x32_bf16 v[2:5], v[100:103], v[108:111], v[2:5]
	s_add_i32 s9, s9, 8
	s_addk_i32 s22, 0x100
	s_cmp_gt_i32 s9, 163
	s_cbranch_scc1 .Lmy_sv4_done
	v_mfma_f32_16x16x32_bf16 v[14:17], v[112:115], v[120:123], v[14:17]
	v_mfma_f32_16x16x32_bf16 v[10:13], v[116:119], v[120:123], v[10:13]
	v_mfma_f32_16x16x32_bf16 v[6:9], v[112:115], v[124:127], v[6:9]
	v_mfma_f32_16x16x32_bf16 v[2:5], v[116:119], v[124:127], v[2:5]
	s_add_i32 s9, s9, 8
	s_addk_i32 s22, 0x100
	s_cmp_gt_i32 s9, 163
	s_cbranch_scc1 .Lmy_sv4_done
	s_branch .Lmy_sv4_done
.Lmy_sv4_tail1:
	s_waitcnt vmcnt(0)
	v_mfma_f32_16x16x32_bf16 v[14:17], v[80:83], v[88:91], v[14:17]
	v_mfma_f32_16x16x32_bf16 v[10:13], v[84:87], v[88:91], v[10:13]
	v_mfma_f32_16x16x32_bf16 v[6:9], v[80:83], v[92:95], v[6:9]
	v_mfma_f32_16x16x32_bf16 v[2:5], v[84:87], v[92:95], v[2:5]
	s_add_i32 s9, s9, 8
	s_addk_i32 s22, 0x100
	s_cmp_gt_i32 s9, 163
	s_cbranch_scc1 .Lmy_sv4_done
	v_mfma_f32_16x16x32_bf16 v[14:17], v[96:99], v[104:107], v[14:17]
	v_mfma_f32_16x16x32_bf16 v[10:13], v[100:103], v[104:107], v[10:13]
	v_mfma_f32_16x16x32_bf16 v[6:9], v[96:99], v[108:111], v[6:9]
	v_mfma_f32_16x16x32_bf16 v[2:5], v[100:103], v[108:111], v[2:5]
	s_add_i32 s9, s9, 8
	s_addk_i32 s22, 0x100
	s_cmp_gt_i32 s9, 163
	s_cbranch_scc1 .Lmy_sv4_done
	v_mfma_f32_16x16x32_bf16 v[14:17], v[112:115], v[120:123], v[14:17]
	v_mfma_f32_16x16x32_bf16 v[10:13], v[116:119], v[120:123], v[10:13]
	v_mfma_f32_16x16x32_bf16 v[6:9], v[112:115], v[124:127], v[6:9]
	v_mfma_f32_16x16x32_bf16 v[2:5], v[116:119], v[124:127], v[2:5]
	s_add_i32 s9, s9, 8
	s_addk_i32 s22, 0x100
	s_cmp_gt_i32 s9, 163
	s_cbranch_scc1 .Lmy_sv4_done
	v_mfma_f32_16x16x32_bf16 v[14:17], v[48:51], v[56:59], v[14:17]
	v_mfma_f32_16x16x32_bf16 v[10:13], v[52:55], v[56:59], v[10:13]
	v_mfma_f32_16x16x32_bf16 v[6:9], v[48:51], v[60:63], v[6:9]
	v_mfma_f32_16x16x32_bf16 v[2:5], v[52:55], v[60:63], v[2:5]
	s_add_i32 s9, s9, 8
	s_addk_i32 s22, 0x100
	s_cmp_gt_i32 s9, 163
	s_cbranch_scc1 .Lmy_sv4_done
	s_branch .Lmy_sv4_done
.Lmy_sv4_tail2:
	s_waitcnt vmcnt(0)
	v_mfma_f32_16x16x32_bf16 v[14:17], v[96:99], v[104:107], v[14:17]
	v_mfma_f32_16x16x32_bf16 v[10:13], v[100:103], v[104:107], v[10:13]
	v_mfma_f32_16x16x32_bf16 v[6:9], v[96:99], v[108:111], v[6:9]
	v_mfma_f32_16x16x32_bf16 v[2:5], v[100:103], v[108:111], v[2:5]
	s_add_i32 s9, s9, 8
	s_addk_i32 s22, 0x100
	s_cmp_gt_i32 s9, 163
	s_cbranch_scc1 .Lmy_sv4_done
	v_mfma_f32_16x16x32_bf16 v[14:17], v[112:115], v[120:123], v[14:17]
	v_mfma_f32_16x16x32_bf16 v[10:13], v[116:119], v[120:123], v[10:13]
	v_mfma_f32_16x16x32_bf16 v[6:9], v[112:115], v[124:127], v[6:9]
	v_mfma_f32_16x16x32_bf16 v[2:5], v[116:119], v[124:127], v[2:5]
	s_add_i32 s9, s9, 8
	s_addk_i32 s22, 0x100
	s_cmp_gt_i32 s9, 163
	s_cbranch_scc1 .Lmy_sv4_done
	v_mfma_f32_16x16x32_bf16 v[14:17], v[48:51], v[56:59], v[14:17]
	v_mfma_f32_16x16x32_bf16 v[10:13], v[52:55], v[56:59], v[10:13]
	v_mfma_f32_16x16x32_bf16 v[6:9], v[48:51], v[60:63], v[6:9]
	v_mfma_f32_16x16x32_bf16 v[2:5], v[52:55], v[60:63], v[2:5]
	s_add_i32 s9, s9, 8
	s_addk_i32 s22, 0x100
	s_cmp_gt_i32 s9, 163
	s_cbranch_scc1 .Lmy_sv4_done
	v_mfma_f32_16x16x32_bf16 v[14:17], v[64:67], v[72:75], v[14:17]
	v_mfma_f32_16x16x32_bf16 v[10:13], v[68:71], v[72:75], v[10:13]
	v_mfma_f32_16x16x32_bf16 v[6:9], v[64:67], v[76:79], v[6:9]
	v_mfma_f32_16x16x32_bf16 v[2:5], v[68:71], v[76:79], v[2:5]
	s_add_i32 s9, s9, 8
	s_addk_i32 s22, 0x100
	s_cmp_gt_i32 s9, 163
	s_cbranch_scc1 .Lmy_sv4_done
	s_branch .Lmy_sv4_done
.Lmy_sv4_tail3:
	s_waitcnt vmcnt(0)
	v_mfma_f32_16x16x32_bf16 v[14:17], v[112:115], v[120:123], v[14:17]
	v_mfma_f32_16x16x32_bf16 v[10:13], v[116:119], v[120:123], v[10:13]
	v_mfma_f32_16x16x32_bf16 v[6:9], v[112:115], v[124:127], v[6:9]
	v_mfma_f32_16x16x32_bf16 v[2:5], v[116:119], v[124:127], v[2:5]
	s_add_i32 s9, s9, 8
	s_addk_i32 s22, 0x100
	s_cmp_gt_i32 s9, 163
	s_cbranch_scc1 .Lmy_sv4_done
	v_mfma_f32_16x16x32_bf16 v[14:17], v[48:51], v[56:59], v[14:17]
	v_mfma_f32_16x16x32_bf16 v[10:13], v[52:55], v[56:59], v[10:13]
	v_mfma_f32_16x16x32_bf16 v[6:9], v[48:51], v[60:63], v[6:9]
	v_mfma_f32_16x16x32_bf16 v[2:5], v[52:55], v[60:63], v[2:5]
	s_add_i32 s9, s9, 8
	s_addk_i32 s22, 0x100
	s_cmp_gt_i32 s9, 163
	s_cbranch_scc1 .Lmy_sv4_done
	v_mfma_f32_16x16x32_bf16 v[14:17], v[64:67], v[72:75], v[14:17]
	v_mfma_f32_16x16x32_bf16 v[10:13], v[68:71], v[72:75], v[10:13]
	v_mfma_f32_16x16x32_bf16 v[6:9], v[64:67], v[76:79], v[6:9]
	v_mfma_f32_16x16x32_bf16 v[2:5], v[68:71], v[76:79], v[2:5]
	s_add_i32 s9, s9, 8
	s_addk_i32 s22, 0x100
	s_cmp_gt_i32 s9, 163
	s_cbranch_scc1 .Lmy_sv4_done
	v_mfma_f32_16x16x32_bf16 v[14:17], v[80:83], v[88:91], v[14:17]
	v_mfma_f32_16x16x32_bf16 v[10:13], v[84:87], v[88:91], v[10:13]
	v_mfma_f32_16x16x32_bf16 v[6:9], v[80:83], v[92:95], v[6:9]
	v_mfma_f32_16x16x32_bf16 v[2:5], v[84:87], v[92:95], v[2:5]
	s_add_i32 s9, s9, 8
	s_addk_i32 s22, 0x100
	s_cmp_gt_i32 s9, 163
	s_cbranch_scc1 .Lmy_sv4_done
	s_branch .Lmy_sv4_done
.Lmy_sv4_tail4:
	s_waitcnt vmcnt(0)
	v_mfma_f32_16x16x32_bf16 v[14:17], v[48:51], v[56:59], v[14:17]
	v_mfma_f32_16x16x32_bf16 v[10:13], v[52:55], v[56:59], v[10:13]
	v_mfma_f32_16x16x32_bf16 v[6:9], v[48:51], v[60:63], v[6:9]
	v_mfma_f32_16x16x32_bf16 v[2:5], v[52:55], v[60:63], v[2:5]
	s_add_i32 s9, s9, 8
	s_addk_i32 s22, 0x100
	s_cmp_gt_i32 s9, 163
	s_cbranch_scc1 .Lmy_sv4_done
	v_mfma_f32_16x16x32_bf16 v[14:17], v[64:67], v[72:75], v[14:17]
	v_mfma_f32_16x16x32_bf16 v[10:13], v[68:71], v[72:75], v[10:13]
	v_mfma_f32_16x16x32_bf16 v[6:9], v[64:67], v[76:79], v[6:9]
	v_mfma_f32_16x16x32_bf16 v[2:5], v[68:71], v[76:79], v[2:5]
	s_add_i32 s9, s9, 8
	s_addk_i32 s22, 0x100
	s_cmp_gt_i32 s9, 163
	s_cbranch_scc1 .Lmy_sv4_done
	v_mfma_f32_16x16x32_bf16 v[14:17], v[80:83], v[88:91], v[14:17]
	v_mfma_f32_16x16x32_bf16 v[10:13], v[84:87], v[88:91], v[10:13]
	v_mfma_f32_16x16x32_bf16 v[6:9], v[80:83], v[92:95], v[6:9]
	v_mfma_f32_16x16x32_bf16 v[2:5], v[84:87], v[92:95], v[2:5]
	s_add_i32 s9, s9, 8
	s_addk_i32 s22, 0x100
	s_cmp_gt_i32 s9, 163
	s_cbranch_scc1 .Lmy_sv4_done
	v_mfma_f32_16x16x32_bf16 v[14:17], v[96:99], v[104:107], v[14:17]
	v_mfma_f32_16x16x32_bf16 v[10:13], v[100:103], v[104:107], v[10:13]
	v_mfma_f32_16x16x32_bf16 v[6:9], v[96:99], v[108:111], v[6:9]
	v_mfma_f32_16x16x32_bf16 v[2:5], v[100:103], v[108:111], v[2:5]
	s_add_i32 s9, s9, 8
	s_addk_i32 s22, 0x100
	s_cmp_gt_i32 s9, 163
	s_cbranch_scc1 .Lmy_sv4_done
	s_branch .Lmy_sv4_done
